# o28 with the MIX1 queue split at indexer item 192 (strict LPT: all indexer items heavier than a GDN item first)
# speedup vs baseline: 1.0273x; 1.0015x over previous
.LBB0_1229:
	s_or_b64 exec, exec, s[0:1]
	s_waitcnt lgkmcnt(0)
	s_barrier
	ds_read_b32 v1, v155
	s_movk_i32 s0, 0x74f
	s_waitcnt lgkmcnt(0)
	v_add_u32_e32 v1, s98, v1
	v_cmp_lt_u32_e32 vcc, s0, v1
	v_readfirstlane_b32 s42, v1
	s_mov_b64 s[0:1], -1
	s_cbranch_vccnz .LBB0_1224
	s_cmpk_gt_u32 s42, 0x2ff
	s_cbranch_scc1 .Lq_nomap
	s_cmpk_lt_u32 s42, 0xc0
	s_cbranch_scc1 .Lq_nomap
	s_cmpk_lt_u32 s42, 0x2c0
	s_cbranch_scc1 .Lq_g1
	s_sub_u32 s42, s42, 0x200
	s_branch .Lq_nomap
.Lq_g1:
	s_add_u32 s42, s42, 0x40
